# conversion queue: next ticket atomicAdd prefetched at the top of the current batch
# speedup vs baseline: 1.0012x; 1.0012x over previous
; #define LAS __attribute__((address_space(3)))
; #define PHASE_PROLOG() CArgs* ka = kargs(); unsigned char* ws = ka->ws; (void)ws; const int tid = opaque_tid(), lane = tid & 63, wave = __builtin_amdgcn_readfirstlane(tid >> 6), gw = vcu * NWAVES + wave; (void)lane; (void)gw
; __global__ void __launch_bounds__(NWAVES * 64, 2) fwd_kernel(Args args_unused) {
;     ...
;             PHASE_PROLOG();
;             LAS float* scr = (LAS float*)(lds + wave * TR_SCR);
;             unsigned* qhead = (unsigned*)(ws + WS_CTL) + CW_QUEUE + 64 * layer;
;             CV_PTRS(P, ka, ws, layer);
;             volatile LAS unsigned* qb = (volatile LAS unsigned*)(lds + MISC_OFF) + 2;
;             for (;;) {
;                 __syncthreads();
;                 if (tid == 0) *qb = atomicAdd(qhead, 32u);
.LBB0_1282:
	v_readlane_b32 s6, v254, 0
	v_readlane_b32 s7, v254, 1
	v_mov_b32_e32 v6, v0
	s_load_dwordx2 s[52:53], s[6:7], 0x98
	s_load_dwordx4 s[24:27], s[6:7], 0x20
	v_readfirstlane_b32 s8, v6
	s_ashr_i32 s39, s8, 6
	s_mul_i32 s8, s39, 0x4200
	s_add_i32 s50, s8, 0
	v_readlane_b32 s8, v254, 63
	v_readlane_b32 s9, v255, 0
	s_lshl_b32 s28, s8, 6
	s_lshl_b64 s[8:9], s[28:29], 2
	s_waitcnt lgkmcnt(0)
	s_add_u32 s8, s52, s8
	s_addc_u32 s9, s53, s9
	s_add_u32 s36, s8, 0x2000
	s_addc_u32 s37, s9, 0
	s_load_dwordx16 s[8:23], s[6:7], 0x50
	v_readlane_b32 s6, v254, 59
	v_readlane_b32 s7, v254, 60
	s_lshl_b64 s[6:7], s[6:7], 2
	s_add_u32 s26, s26, s6
	s_addc_u32 s27, s27, s7
	v_readlane_b32 s6, v254, 61
	v_readlane_b32 s7, v254, 62
	s_lshl_b64 s[6:7], s[6:7], 2
	s_waitcnt lgkmcnt(0)
	s_add_u32 s22, s22, s6
	s_addc_u32 s23, s23, s7
	v_readlane_b32 s6, v255, 5
	v_readlane_b32 s7, v255, 6
	s_lshl_b64 s[6:7], s[6:7], 2
	s_add_u32 s40, s8, s6
	s_addc_u32 s41, s9, s7
	s_lshl_b64 s[8:9], s[48:49], 2
	s_add_u32 s12, s12, s8
	s_addc_u32 s13, s13, s9
	s_add_u32 s14, s14, s8
	s_addc_u32 s15, s15, s9
	s_add_u32 s16, s16, s8
	s_addc_u32 s17, s17, s9
	s_add_u32 s20, s20, s6
	s_addc_u32 s21, s21, s7
	v_readlane_b32 s6, v254, 57
	v_readlane_b32 s7, v254, 58
	s_lshl_b64 s[6:7], s[6:7], 2
	s_add_u32 s8, s24, s6
	s_addc_u32 s9, s25, s7
	s_add_u32 s34, s10, s6
	s_addc_u32 s35, s11, s7
	v_readlane_b32 s10, v255, 3
	s_add_u32 s42, s18, s6
	v_readlane_b32 s11, v255, 4
	s_addc_u32 s43, s19, s7
	s_lshl_b64 s[10:11], s[10:11], 2
	s_add_u32 s46, s52, s10
	s_addc_u32 s47, s53, s11
	s_add_u32 s10, s52, 0x6c510000
	s_addc_u32 s11, s53, 0
	s_add_u32 s48, s52, s6
	s_addc_u32 s49, s53, s7
	v_readlane_b32 s6, v255, 1
	s_add_u32 s18, s52, 0x6c525800
	v_readlane_b32 s7, v255, 2
	s_addc_u32 s19, s53, 0
	s_lshl_b64 s[6:7], s[6:7], 2
	s_add_u32 s54, s52, s6
	s_waitcnt vmcnt(16)
	v_and_b32_e32 v122, 7, v6
	v_bfe_u32 v80, v6, 3, 3
	s_addc_u32 s55, s53, s7
	v_cmp_eq_u32_e64 s[6:7], 0, v6
	s_waitcnt vmcnt(1)
	v_bfe_u32 v77, v6, 4, 2
	v_lshlrev_b32_e32 v2, 2, v6
	v_lshlrev_b32_e32 v4, 5, v122
	v_mov_b32_e32 v5, v3
	v_lshlrev_b32_e32 v6, 2, v80
	v_mov_b32_e32 v7, v3
	v_and_b32_e32 v76, 60, v2
	v_lshl_add_u64 v[78:79], s[42:43], 0, v[4:5]
	v_lshl_add_u64 v[8:9], s[48:49], 0, v[6:7]
	s_mov_b64 s[42:43], 0xc0000
	v_lshlrev_b32_e32 v2, 3, v122
	v_lshl_add_u64 v[82:83], v[8:9], 0, s[42:43]
	v_mul_u32_u24_e32 v8, 0x104, v77
	v_lshlrev_b32_e32 v9, 2, v76
	v_lshl_add_u64 v[102:103], s[34:35], 0, v[4:5]
	v_lshl_add_u64 v[12:13], s[46:47], 0, v[6:7]
	s_mov_b64 s[34:35], 0x4ac00
	s_add_u32 s44, s52, 0x6c529800
	v_add3_u32 v123, s50, v8, v9
	v_lshl_add_u64 v[8:9], s[52:53], 0, v[2:3]
	v_lshl_add_u64 v[104:105], v[12:13], 0, s[34:35]
	s_mov_b64 s[34:35], 0x9200000
	s_addc_u32 s45, s53, 0
	v_mul_u32_u24_e32 v10, 0x820, v122
	v_lshlrev_b32_e32 v2, 4, v122
	v_lshl_add_u64 v[106:107], v[8:9], 0, s[34:35]
	s_mov_b64 s[34:35], 0x40000
	v_lshl_add_u64 v[114:115], s[8:9], 0, v[4:5]
	v_lshl_add_u64 v[4:5], s[54:55], 0, v[6:7]
	s_mov_b64 s[8:9], 0x80000
	s_mov_b64 s[42:43], 0x19400000
	v_add3_u32 v124, s50, v10, v6
	v_lshl_add_u64 v[10:11], s[52:53], 0, v[2:3]
	v_lshl_add_u64 v[108:109], v[12:13], 0, s[34:35]
	s_mov_b64 s[34:35], 0x7200000
	s_cmp_eq_u64 s[24:25], 0
	v_lshl_add_u64 v[116:117], v[4:5], 0, s[8:9]
	s_mov_b64 s[8:9], 0x6c52f800
	v_lshl_add_u64 v[84:85], v[8:9], 0, s[42:43]
	s_mov_b64 s[42:43], 0x13e00000
	v_lshl_add_u64 v[110:111], v[10:11], 0, s[34:35]
	s_mov_b64 s[34:35], 0x1b400000
	s_cselect_b64 s[50:51], -1, 0
	s_cmp_lg_u64 s[24:25], 0
	v_lshl_add_u64 v[118:119], v[8:9], 0, s[8:9]
	s_mov_b64 s[8:9], 0x200000
	v_mov_b32_e32 v81, v3
	v_or_b32_e32 v86, 8, v80
	v_or_b32_e32 v88, 16, v80
	v_or_b32_e32 v90, 24, v80
	v_or_b32_e32 v92, 32, v80
	v_or_b32_e32 v94, 40, v80
	v_or_b32_e32 v96, 48, v80
	v_or_b32_e32 v98, 56, v80
	v_lshl_add_u64 v[100:101], v[10:11], 0, s[42:43]
	v_lshl_add_u64 v[112:113], v[10:11], 0, s[34:35]
	s_cselect_b64 s[24:25], -1, 0
	v_mov_b32_e32 v87, v3
	v_mov_b32_e32 v89, v3
	v_mov_b32_e32 v91, v3
	v_mov_b32_e32 v93, v3
	v_mov_b32_e32 v95, v3
	v_mov_b32_e32 v97, v3
	v_mov_b32_e32 v99, v3
	v_lshl_add_u64 v[120:121], v[10:11], 0, s[8:9]
	s_addk_i32 s39, 0x3900
	s_and_saveexec_b64 s[8:9], s[6:7]
	s_cbranch_execz .Lq_pre_skip
	v_mov_b32_e32 v160, 32
	global_atomic_add v160, v3, v160, s[36:37] sc0
.Lq_pre_skip:
	s_mov_b64 exec, s[8:9]
	s_branch .LBB0_1285

; __global__ void __launch_bounds__(NWAVES * 64, 2) fwd_kernel(Args args_unused) {
;     ...
;                 __syncthreads();
;                 if (tid == 0) *qb = atomicAdd(qhead, 32u);
;                 __syncthreads();
;                 const int it0 = CV_A + (int)__builtin_amdgcn_readfirstlane(*qb);
.LBB0_1288:
	s_or_b64 exec, exec, s[34:35]
	s_waitcnt vmcnt(0)
	v_readfirstlane_b32 s28, v160
	s_nop 1
	v_lshl_add_u32 v2, v2, 5, s28
	v_readlane_b32 s28, v254, 41
	s_nop 1
	v_mov_b32_e32 v4, s28
	ds_write_b32 v4, v2
	v_mov_b32_e32 v160, 32
	global_atomic_add v160, v3, v160, s[36:37] sc0
